# attention unit order: B units interleaved one per two cost-ordered A/C units instead of all last (smallest A/C unit still last)
# baseline (speedup 1.0000x reference)
; DI void prologue(const Args& a, LAS unsigned char* lds, int gw, int NGW, int wave, int lane) {
;     ...
;         while (ia < 128 || ic0 < 64 || ic1 < 64) {
;             const int t0 = 4 * (64 - ic0), t1 = 4 * (64 - ic1);
;             const int ca = ia < 128 ? 48 * (128 - ia) : -1, c0 = ic0 < 64 ? 24 * (t0 < nh[0] ? t0 : nh[0]) : -1, c1 = ic1 < 64 ? 24 * (t1 < nh[1] ? t1 : nh[1]) : -1;
;             if (ca >= c0 && ca >= c1) { const int qa = 127 - ia; tab[pos++] = (0u << 28) | ((unsigned)(q >> 2) << 24) | ((unsigned)(q & 3) << 16) | (unsigned)qa; ++ia; }
;             else if (c0 >= c1) { const int qc = 63 - ic0, bh = 2 * q; tab[pos++] = (2u << 28) | ((unsigned)(bh >> 3) << 24) | ((unsigned)(bh & 7) << 16) | (unsigned)qc; ++ic0; }
;             else { const int qc = 63 - ic1, bh = 2 * q + 1; tab[pos++] = (2u << 28) | ((unsigned)(bh >> 3) << 24) | ((unsigned)(bh & 7) << 16) | (unsigned)qc; ++ic1; }
;         }
.Lord_loop:
	v_add_u32_e32 v33, s8, v28
	v_lshlrev_b32_e32 v34, 1, v33
	v_lshlrev_b32_e32 v35, 2, v33
	v_sub_u32_e32 v34, 0x100, v34
	v_sub_u32_e32 v35, 0x100, v35
	v_min_i32_e32 v35, v35, v29
	v_cndmask_b32_e64 v34, v35, v34, s[4:5]
	v_cmp_gt_i32_e32 vcc, v10, v34
	v_cmp_gt_i32_e64 s[10:11], v11, v34
	v_cmp_ge_i32_e64 s[12:13], v10, v34
	v_sub_u32_e32 v35, 0x103, v34
	v_sub_u32_e32 v38, 0x100, v34
	v_lshrrev_b32_e32 v35, 2, v35
	v_lshrrev_b32_e32 v39, 2, v38
	v_lshrrev_b32_e32 v38, 1, v38
	v_add_u32_e32 v39, 1, v39
	v_add_u32_e32 v38, 1, v38
	v_cndmask_b32_e32 v36, 0, v35, vcc
	v_cndmask_b32_e64 v37, 0, v35, s[10:11]
	v_cndmask_b32_e64 v39, 0, v39, s[12:13]
	v_cndmask_b32_e64 v36, v38, v36, s[4:5]
	v_cndmask_b32_e64 v37, v37, v39, s[6:7]
	v_add3_u32 v36, v33, v36, v37
	v_lshrrev_b32_e32 v38, 1, v36
	v_add3_u32 v36, v36, v38, 1
	v_sub_u32_e32 v37, v31, v33
	v_lshlrev_b32_e32 v36, 2, v36
	v_or_b32_e32 v37, v37, v30
	v_add_co_u32_e32 v40, vcc, v6, v36
	s_nop 1
	v_addc_co_u32_e32 v41, vcc, 0, v7, vcc
	global_store_dword v[40:41], v37, off
	s_add_i32 s8, s8, 1
	s_cmp_lt_u32 s8, 64
	s_cbranch_scc1 .Lord_loop

; DI void prologue(const Args& a, LAS unsigned char* lds, int gw, int NGW, int wave, int lane) {
;     ...
;         for (int i = 0; i < 128; ++i) { const int qb = i / 2, bh = 2 * q + (i & 1); tab[256 + i] = (1u << 28) | ((unsigned)(bh >> 3) << 24) | ((unsigned)(bh & 7) << 16) | (unsigned)qb; }
.LBB0_705:
	s_mov_b32 s97, s96
	s_add_i32 s10, s3, 2
	s_add_i32 s11, s2, 2
	s_add_i32 s12, s3, 4
	s_add_i32 s13, s2, 4
	s_add_i32 s14, s3, 6
	s_add_i32 s15, s2, 6
	s_add_i32 s16, s3, 8
	s_add_i32 s17, s2, 8
	s_add_i32 s18, s3, 10
	s_add_i32 s19, s2, 10
	s_add_i32 s20, s3, 12
	s_add_i32 s22, s2, 12
	s_add_i32 s23, s3, 14
	s_add_i32 s24, s2, 14
	s_lshr_b32 s8, s2, 1
	s_lshr_b32 s9, s3, 1
	s_and_b64 s[6:7], s[2:3], s[96:97]
	s_lshr_b32 s11, s11, 1
	s_lshr_b32 s10, s10, 1
	s_lshr_b32 s13, s13, 1
	s_lshr_b32 s12, s12, 1
	s_lshr_b32 s15, s15, 1
	s_lshr_b32 s14, s14, 1
	s_lshr_b32 s17, s17, 1
	s_lshr_b32 s16, s16, 1
	s_lshr_b32 s19, s19, 1
	s_lshr_b32 s18, s18, 1
	s_lshr_b32 s22, s22, 1
	s_lshr_b32 s20, s20, 1
	s_lshr_b32 s24, s24, 1
	s_lshr_b32 s23, s23, 1
	s_add_i32 s2, s2, 16
	s_add_i32 s3, s3, 16
	v_lshl_add_u64 v[8:9], v[4:5], 0, s[4:5]
	s_mov_b32 s25, 0x100000
	s_add_u32 s4, s4, 0xc0
	v_add_co_u32_e32 v24, vcc, s25, v8
	v_or_b32_sdwa v7, s7, v3 dst_sel:WORD_1 dst_unused:UNUSED_PAD src0_sel:DWORD src1_sel:DWORD
	v_or_b32_sdwa v22, s6, v0 dst_sel:WORD_1 dst_unused:UNUSED_PAD src0_sel:DWORD src1_sel:DWORD
	s_addc_u32 s5, s5, 0
	v_addc_co_u32_e32 v25, vcc, 0, v9, vcc
	v_add3_u32 v9, v1, s9, v7
	v_add3_u32 v8, v6, s8, v22
	v_add3_u32 v11, v1, s10, v7
	v_add3_u32 v10, v6, s11, v22
	v_add3_u32 v12, v6, s13, v22
	v_add3_u32 v14, v6, s15, v22
	v_add3_u32 v16, v6, s17, v22
	v_add3_u32 v18, v6, s19, v22
	v_add3_u32 v21, v1, s20, v7
	v_add3_u32 v20, v6, s22, v22
	v_add3_u32 v23, v1, s23, v7
	v_add3_u32 v22, v6, s24, v22
	s_cmpk_lg_i32 s4, 0x600
	v_add3_u32 v13, v1, s12, v7
	v_add3_u32 v15, v1, s14, v7
	v_add3_u32 v17, v1, s16, v7
	v_add3_u32 v19, v1, s18, v7
	global_store_dword v[24:25], v8, off
	global_store_dword v[24:25], v9, off offset:12
	global_store_dword v[24:25], v10, off offset:24
	global_store_dword v[24:25], v11, off offset:36
	global_store_dword v[24:25], v12, off offset:48
	global_store_dword v[24:25], v13, off offset:60
	global_store_dword v[24:25], v14, off offset:72
	global_store_dword v[24:25], v15, off offset:84
	global_store_dword v[24:25], v16, off offset:96
	global_store_dword v[24:25], v17, off offset:108
	global_store_dword v[24:25], v18, off offset:120
	global_store_dword v[24:25], v19, off offset:132
	global_store_dword v[24:25], v20, off offset:144
	global_store_dword v[24:25], v21, off offset:156
	global_store_dword v[24:25], v22, off offset:168
	global_store_dword v[24:25], v23, off offset:180
	s_cbranch_scc1 .LBB0_705
